# P3: the workgroup's 128 selection rows are handed out dynamically through an LDS ticket counter (largest t first) instead of 16 fixed rows per wave; cmp tasks unchanged
# speedup vs baseline: 1.0076x; 1.0049x over previous
; __global__ void __launch_bounds__(NTHR, 2) fwd_kernel(Args a) {
;     ...
;     {
;         const int nrow = (MTOK - gw + NGW - 1) / NGW, ncmp = (8192 - gw + NGW - 1) / NGW;
;         const int stride = nrow > 0 && ncmp > 0 ? (nrow / ncmp > 0 ? nrow / ncmp : 1) : 1, phase = ((wave >> 2) * (stride >> 1) + (wave & 1)) % stride;
;         int ci = 0;
.LBB0_472:
	s_or_b64 exec, exec, s[4:5]
	s_sub_i32 s4, s20, s92
	s_add_i32 s5, s4, 0x7fff
	s_sub_i32 s7, 0xffff8001, s4
	s_ashr_i32 s6, s5, 31
	s_max_i32 s5, s5, s7
	s_mul_hi_u32 s7, s5, s73
	s_mul_i32 s8, s7, s21
	s_sub_i32 s5, s5, s8
	s_xor_b32 s6, s6, s72
	s_add_i32 s8, s7, 1
	s_sub_i32 s9, s5, s21
	s_cmp_ge_u32 s5, s21
	s_cselect_b32 s7, s8, s7
	s_cselect_b32 s5, s9, s5
	s_add_i32 s8, s7, 1
	s_cmp_ge_u32 s5, s21
	s_cselect_b32 s5, s8, s7
	s_xor_b32 s5, s5, s6
	s_sub_i32 s47, s5, s6
	s_add_i32 s5, s4, 0x1fff
	s_sub_i32 s4, 0xffffe001, s4
	s_max_i32 s4, s5, s4
	s_ashr_i32 s6, s5, 31
	s_mul_hi_u32 s5, s4, s73
	s_mul_i32 s7, s5, s21
	s_sub_i32 s4, s4, s7
	s_xor_b32 s6, s6, s72
	s_add_i32 s7, s5, 1
	s_sub_i32 s8, s4, s21
	s_cmp_ge_u32 s4, s21
	s_cselect_b32 s5, s7, s5
	s_cselect_b32 s4, s8, s4
	s_add_i32 s7, s5, 1
	s_cmp_ge_u32 s4, s21
	s_cselect_b32 s4, s7, s5
	s_xor_b32 s4, s4, s6
	s_sub_i32 s58, s4, s6
	s_cmp_gt_i32 s47, 0
	s_cselect_b64 s[8:9], -1, 0
	s_cmp_gt_i32 s58, 0
	s_cselect_b64 s[10:11], -1, 0
	s_and_b64 s[4:5], s[8:9], s[10:11]
	s_mov_b32 s69, 1
	s_and_b64 vcc, exec, s[4:5]
	v_mov_b32_e32 v1, 0
	ds_write_b32 v1, v1
	s_waitcnt lgkmcnt(0)
	s_barrier
	s_cbranch_vccz .LBB0_474
	v_cvt_f32_u32_e32 v1, s58
	s_sub_i32 s4, 0, s58
	v_rcp_iflag_f32_e32 v1, v1
	s_nop 0
	v_mul_f32_e32 v1, 0x4f7ffffe, v1
	v_cvt_u32_f32_e32 v1, v1
	s_nop 0
	v_readfirstlane_b32 s5, v1
	s_mul_i32 s4, s4, s5
	s_mul_hi_u32 s4, s5, s4
	s_add_i32 s5, s5, s4
	s_mul_hi_u32 s4, s47, s5
	s_mul_i32 s5, s4, s58
	s_sub_i32 s5, s47, s5
	s_add_i32 s6, s4, 1
	s_sub_i32 s7, s5, s58
	s_cmp_ge_u32 s5, s58
	s_cselect_b32 s4, s6, s4
	s_cselect_b32 s5, s7, s5
	s_add_i32 s6, s4, 1
	s_cmp_ge_u32 s5, s58
	s_cselect_b32 s4, s6, s4
	s_cmp_le_u32 s58, s47
	s_cselect_b32 s69, s4, 1
.LBB0_474:
	v_cvt_f32_u32_e32 v1, s69
	s_add_u32 s21, s18, 0x6000000
	s_addc_u32 s68, s19, 0
	s_add_u32 s12, s18, 0x6800000
	v_rcp_iflag_f32_e32 v1, v1
	s_addc_u32 s13, s19, 0
	s_or_b64 s[4:5], s[8:9], s[10:11]
	s_andn2_b64 vcc, exec, s[4:5]
	v_mul_f32_e32 v1, 0x4f7ffffe, v1
	v_cvt_u32_f32_e32 v1, v1
	s_nop 0
	v_readfirstlane_b32 s59, v1
	s_cbranch_vccnz .LBB0_659
	v_lshlrev_b32_e32 v1, 6, v133
	v_or_b32_e32 v37, 47, v1
	v_or_b32_e32 v46, 31, v1
	v_or_b32_e32 v117, 63, v1
	v_add_u32_e32 v119, 0x4f, v1
	v_or_b32_e32 v39, 0xaf, v1
	v_or_b32_e32 v48, 0x9f, v1
	v_or_b32_e32 v202, 0xbf, v1
	v_add_u32_e32 v203, 0xcf, v1
	v_or_b32_e32 v47, 0x12f, v1
	v_or_b32_e32 v50, 0x11f, v1
	v_or_b32_e32 v204, 0x13f, v1
	v_add_u32_e32 v205, 0x14f, v1
	v_or_b32_e32 v49, 0x1af, v1
	v_or_b32_e32 v52, 0x19f, v1
	v_or_b32_e32 v206, 0x1bf, v1
	v_add_u32_e32 v207, 0x1cf, v1
	v_or_b32_e32 v51, 0x22f, v1
	v_or_b32_e32 v54, 0x21f, v1
	v_or_b32_e32 v208, 0x23f, v1
	v_add_u32_e32 v209, 0x24f, v1
	v_or_b32_e32 v53, 0x2af, v1
	v_or_b32_e32 v56, 0x29f, v1
	v_or_b32_e32 v210, 0x2bf, v1
	v_add_u32_e32 v211, 0x2cf, v1
	v_or_b32_e32 v55, 0x32f, v1
	v_or_b32_e32 v58, 0x31f, v1
	v_or_b32_e32 v212, 0x33f, v1
	v_add_u32_e32 v213, 0x34f, v1
	v_or_b32_e32 v57, 0x3af, v1
	v_or_b32_e32 v60, 0x39f, v1
	v_or_b32_e32 v216, 0x3bf, v1
	v_add_u32_e32 v217, 0x3cf, v1
	v_or_b32_e32 v59, 0x42f, v1
	v_or_b32_e32 v62, 0x41f, v1
	v_or_b32_e32 v218, 0x43f, v1
	v_add_u32_e32 v219, 0x44f, v1
	v_or_b32_e32 v61, 0x4af, v1
	v_or_b32_e32 v64, 0x49f, v1
	v_or_b32_e32 v220, 0x4bf, v1
	v_add_u32_e32 v221, 0x4cf, v1
	v_or_b32_e32 v63, 0x52f, v1
	v_or_b32_e32 v66, 0x51f, v1
	v_or_b32_e32 v222, 0x53f, v1
	v_add_u32_e32 v223, 0x54f, v1
	v_or_b32_e32 v65, 0x5af, v1
	v_or_b32_e32 v68, 0x59f, v1
	v_or_b32_e32 v224, 0x5bf, v1
	v_add_u32_e32 v225, 0x5cf, v1
	v_or_b32_e32 v67, 0x62f, v1
	v_or_b32_e32 v70, 0x61f, v1
	v_or_b32_e32 v226, 0x63f, v1
	v_add_u32_e32 v227, 0x64f, v1
	v_or_b32_e32 v69, 0x6af, v1
	v_or_b32_e32 v72, 0x69f, v1
	v_or_b32_e32 v228, 0x6bf, v1
	v_add_u32_e32 v229, 0x6cf, v1
	v_or_b32_e32 v71, 0x72f, v1
	v_or_b32_e32 v74, 0x71f, v1
	v_or_b32_e32 v230, 0x73f, v1
	v_add_u32_e32 v231, 0x74f, v1
	v_or_b32_e32 v73, 0x7af, v1
	v_or_b32_e32 v76, 0x79f, v1
	v_or_b32_e32 v232, 0x7bf, v1
	v_add_u32_e32 v233, 0x7cf, v1
	v_lshl_or_b32 v1, v214, 3, v133
	v_cmp_lt_u32_e64 s[16:17], 2, v1
	v_cmp_lt_u32_e64 s[26:27], 10, v1
	v_cmp_lt_u32_e64 s[38:39], 18, v1
	v_writelane_b32 v253, s16, 6
	v_mov_b32_e32 v43, 0
	v_lshlrev_b32_e32 v40, 1, v139
	v_writelane_b32 v253, s17, 7
	v_cmp_lt_u32_e64 s[16:17], 4, v1
	v_mov_b32_e32 v41, v43
	v_or_b32_e32 v2, 2, v1
	v_writelane_b32 v253, s16, 8
	v_lshl_add_u64 v[44:45], s[48:49], 0, v[40:41]
	v_cmp_lt_u32_e64 s[48:49], 4, v2
	v_writelane_b32 v253, s17, 9
	v_cmp_lt_u32_e64 s[16:17], 6, v1
	s_lshr_b32 s4, s78, 8
	s_lshr_b32 s5, s69, 1
	v_writelane_b32 v253, s16, 10
	s_mul_i32 s4, s5, s4
	s_bfe_u32 s5, s78, 0x10006
	v_writelane_b32 v253, s17, 11
	v_cmp_lt_u32_e64 s[16:17], 8, v1
	s_add_i32 s4, s4, s5
	s_sub_i32 s5, 0, s69
	v_writelane_b32 v253, s16, 12
	s_mul_i32 s5, s5, s59
	s_mul_hi_u32 s5, s59, s5
	v_writelane_b32 v253, s17, 13
	v_writelane_b32 v253, s26, 14
	s_add_i32 s59, s59, s5
	s_mul_hi_u32 s5, s4, s59
	v_writelane_b32 v253, s27, 15
	v_cmp_lt_u32_e64 s[26:27], 12, v1
	s_mul_i32 s5, s5, s69
	s_sub_i32 s4, s4, s5
	v_writelane_b32 v253, s26, 16
	s_sub_i32 s5, s4, s69
	s_cmp_ge_u32 s4, s69
	v_writelane_b32 v253, s27, 17
	v_cmp_lt_u32_e64 s[26:27], 14, v1
	s_cselect_b32 s4, s5, s4
	s_sub_i32 s5, s4, s69
	v_writelane_b32 v253, s26, 18
	v_cmp_ne_u32_e64 s[6:7], 0, v1
	v_lshlrev_b32_e64 v237, v1, 1
	v_writelane_b32 v253, s27, 19
	v_cmp_lt_u32_e64 s[26:27], 16, v1
	v_lshlrev_b32_e64 v238, v1, 4
	v_lshlrev_b32_e64 v239, v1, 16
	v_writelane_b32 v253, s26, 20
	v_lshlrev_b32_e64 v240, v1, 64
	s_cmp_ge_u32 s4, s69
	v_writelane_b32 v253, s27, 21
; DI void cmp_task(const bf16_t* Z, const bf16_t* KCC, const bf16_t* VCT, bf16_t* OCMP, unsigned* selm, int b, int hk, int tg, int lane) {
;     ...
;         unsigned word = 0u;
; #pragma unroll
;         for (int mm = 0; mm < 4; ++mm) {
;             const int jm = 8 * g + 2 * mm + h; const float v = mine[mm]; int rank = 0;
; #pragma unroll
;             for (int T = 0; T < 4; ++T)
; #pragma unroll
;                 for (int m2 = 0; m2 < 4; ++m2) { const int je = 8 * T + 2 * m2;
;                     rank += (ev[T][m2] > v || (ev[T][m2] == v && je < jm)) ? 1 : 0; rank += (od[T][m2] > v || (od[T][m2] == v && je + 1 < jm)) ? 1 : 0; }
;             if (v >= 0.f && rank < 5) word |= 1u << jm;
	v_writelane_b32 v253, s38, 22
	v_mov_b32_e32 v139, v43
	v_lshlrev_b32_e32 v88, 2, v135
	v_writelane_b32 v253, s39, 23
	v_cmp_lt_u32_e64 s[38:39], 20, v1
	v_lshlrev_b32_e32 v241, 2, v242
	v_cmp_eq_u32_e64 s[74:75], 0, v242
	v_writelane_b32 v253, s38, 24
	v_lshlrev_b32_e32 v242, 5, v135
	s_cselect_b32 s60, s5, s4
	v_writelane_b32 v253, s39, 25
	v_cmp_lt_u32_e64 s[38:39], 22, v1
	v_lshrrev_b32_e32 v113, 2, v134
	v_lshlrev_b32_e32 v115, 6, v214
	v_writelane_b32 v253, s38, 26
	v_lshlrev_b32_e32 v38, 6, v134
	v_lshl_add_u64 v[78:79], s[14:15], 0, v[138:139]
	v_writelane_b32 v253, s39, 27
	v_writelane_b32 v253, s48, 28
	v_cmp_eq_u32_e64 s[38:39], 25, v1
	v_or_b32_e32 v80, 0x1000, v136
	v_writelane_b32 v253, s49, 29
	v_cmp_lt_u32_e64 s[48:49], 5, v2
	v_cmp_gt_u32_e64 s[4:5], 32, v135
	v_or_b32_e32 v84, 20, v133
	v_writelane_b32 v253, s48, 30
	v_or_b32_e32 v36, 18, v133
	v_or_b32_e32 v236, 24, v133
	v_writelane_b32 v253, s49, 31
	v_cmp_lt_u32_e64 s[48:49], 6, v2
	v_or_b32_e32 v81, 28, v133
	s_mov_b32 s15, 0
	v_writelane_b32 v253, s48, 32
	v_cmp_lt_u32_e64 s[16:17], 1, v214
	v_cmp_ne_u32_e64 s[26:27], 0, v214
	v_writelane_b32 v253, s49, 33
	v_cmp_lt_u32_e64 s[48:49], 8, v2
	v_cmp_eq_u32_e64 s[28:29], 3, v214
	v_or_b32_e32 v83, 0x101, v88
	v_writelane_b32 v253, s48, 34
	v_or_b32_e32 v90, 0x100, v88
	v_or_b32_e32 v85, 0x103, v88
	v_writelane_b32 v253, s49, 35
	v_cmp_lt_u32_e64 s[48:49], 9, v2
	v_or_b32_e32 v92, 0x102, v88
	v_or_b32_e32 v87, 0x201, v88
	v_writelane_b32 v253, s48, 36
	v_or_b32_e32 v86, 0x200, v88
	v_or_b32_e32 v89, 0x203, v88
	v_writelane_b32 v253, s49, 37
	v_cmp_lt_u32_e64 s[48:49], 10, v2
	v_or_b32_e32 v91, 0x301, v88
	v_or_b32_e32 v98, 0x300, v88
	v_writelane_b32 v253, s48, 38
	v_or_b32_e32 v93, 0x303, v88
	v_or_b32_e32 v100, 0x302, v88
	v_writelane_b32 v253, s49, 39
	v_cmp_lt_u32_e64 s[48:49], 16, v2
	v_or_b32_e32 v102, 0x400, v88
	v_or_b32_e32 v104, 0x402, v88
	v_writelane_b32 v253, s48, 40
	v_or_b32_e32 v99, 0x501, v88
	v_or_b32_e32 v106, 0x500, v88
	v_writelane_b32 v253, s49, 41
	v_cmp_lt_u32_e64 s[48:49], 12, v2
	v_or_b32_e32 v101, 0x503, v88
	v_or_b32_e32 v108, 0x502, v88
	v_writelane_b32 v253, s48, 42
	v_or_b32_e32 v103, 0x601, v88
	v_or_b32_e32 v110, 0x600, v88
	v_writelane_b32 v253, s49, 43
	v_cmp_lt_u32_e64 s[48:49], 17, v2
	v_or_b32_e32 v105, 0x603, v88
	v_or_b32_e32 v112, 0x602, v88
	v_writelane_b32 v253, s48, 44
	v_or_b32_e32 v107, 0x701, v88
	v_or_b32_e32 v114, 0x700, v88
	v_writelane_b32 v253, s49, 45
	v_cmp_lt_u32_e64 s[48:49], 13, v2
	v_or_b32_e32 v109, 0x703, v88
	v_or_b32_e32 v116, 0x702, v88
	v_writelane_b32 v253, s48, 46
	v_or_b32_e32 v243, 31, v242
	s_mov_b32 s46, 0x3e38aa3b
	v_writelane_b32 v253, s49, 47
	v_cmp_lt_u32_e64 s[48:49], 18, v2
	s_mov_b32 s61, 0xff800000
	s_mov_b32 s62, -1.0
	v_writelane_b32 v253, s48, 48
	v_lshlrev_b32_e32 v120, 2, v88
	v_mov_b32_e32 v244, 0x2200
	v_writelane_b32 v253, s49, 49
	v_cmp_lt_u32_e64 s[48:49], 14, v2
	v_mov_b32_e32 v245, 0xff800000
	s_mov_b32 s63, 0
	v_writelane_b32 v253, s48, 50
	s_mov_b32 s64, 0
	s_nop 0
	v_writelane_b32 v253, s49, 51
	v_cmp_lt_u32_e64 s[48:49], 20, v2
	s_nop 1
	v_writelane_b32 v253, s48, 52
	s_nop 1
	v_writelane_b32 v253, s49, 53
	v_cmp_lt_u32_e64 s[48:49], 21, v2
	s_nop 1
	v_writelane_b32 v253, s48, 54
	s_nop 1
	v_writelane_b32 v253, s49, 55
	v_cmp_lt_u32_e64 s[48:49], 22, v2
	s_nop 1
	v_writelane_b32 v253, s48, 56
	s_nop 1
	v_writelane_b32 v253, s49, 57
	v_cmp_lt_u32_e64 s[48:49], 24, v2
	s_nop 1
	v_writelane_b32 v253, s48, 58
	s_nop 1
	v_writelane_b32 v253, s49, 59
	v_cmp_lt_u32_e64 s[48:49], 25, v2
	v_or_b32_e32 v2, 4, v1
	s_nop 0
	v_writelane_b32 v253, s48, 60
	s_nop 1
	v_writelane_b32 v253, s49, 61
	v_cmp_lt_u32_e64 s[48:49], 5, v2
	s_nop 1
	v_writelane_b32 v253, s48, 62
	s_nop 1
	v_writelane_b32 v253, s49, 63
	v_cmp_lt_u32_e64 s[48:49], 6, v2
	s_nop 1
	v_writelane_b32 v254, s48, 0
	s_nop 1
	v_writelane_b32 v254, s49, 1
	v_cmp_lt_u32_e64 s[48:49], 8, v2
	s_nop 1
	v_writelane_b32 v254, s48, 2
	s_nop 1
	v_writelane_b32 v254, s49, 3
	v_cmp_lt_u32_e64 s[48:49], 9, v2
	s_nop 1
	v_writelane_b32 v254, s48, 4
	s_nop 1
	v_writelane_b32 v254, s49, 5
	v_cmp_lt_u32_e64 s[48:49], 10, v2
	s_nop 1
	v_writelane_b32 v254, s48, 6
	s_nop 1
	v_writelane_b32 v254, s49, 7
	v_cmp_lt_u32_e64 s[48:49], 11, v2
	s_nop 1
	v_writelane_b32 v254, s48, 8
	s_nop 1
	v_writelane_b32 v254, s49, 9
	v_cmp_lt_u32_e64 s[48:49], 12, v2
	s_nop 1
	v_writelane_b32 v254, s48, 10
	s_nop 1
	v_writelane_b32 v254, s49, 11
	v_cmp_lt_u32_e64 s[48:49], 13, v2
	s_nop 1
	v_writelane_b32 v254, s48, 12
; DI void cmp_task(const bf16_t* Z, const bf16_t* KCC, const bf16_t* VCT, bf16_t* OCMP, unsigned* selm, int b, int hk, int tg, int lane) {
;     ...
;         unsigned word = 0u;
; #pragma unroll
;         for (int mm = 0; mm < 4; ++mm) {
;             const int jm = 8 * g + 2 * mm + h; const float v = mine[mm]; int rank = 0;
; #pragma unroll
;             for (int T = 0; T < 4; ++T)
; #pragma unroll
;                 for (int m2 = 0; m2 < 4; ++m2) { const int je = 8 * T + 2 * m2;
;                     rank += (ev[T][m2] > v || (ev[T][m2] == v && je < jm)) ? 1 : 0; rank += (od[T][m2] > v || (od[T][m2] == v && je + 1 < jm)) ? 1 : 0; }
;             if (v >= 0.f && rank < 5) word |= 1u << jm;
; __global__ void __launch_bounds__(NTHR, 2) fwd_kernel(Args a) {
;     ...
;         for (int i = 0; i < nrow || ci < ncmp; ++i) {
;             if (ci < ncmp && (i >= nrow || (i % stride) == phase)) { const int task = gw + ci * NGW; ++ci;
;                 cmp_task(Z, KCC, VCT, OCMP, SELM, task >> 9, (task >> 8) & 1, (task + 64 * (task >> 11)) & 255, lane); }
;             if (i < nrow) { const int r = gw + i * NGW; select_row(SC, DMASK, r & 15, r >> 4, lane); }
	s_nop 1
	v_writelane_b32 v254, s49, 13
	v_cmp_lt_u32_e64 s[48:49], 14, v2
	s_nop 1
	v_writelane_b32 v254, s48, 14
	s_nop 1
	v_writelane_b32 v254, s49, 15
	v_cmp_lt_u32_e64 s[48:49], 16, v2
	s_nop 1
	v_writelane_b32 v254, s48, 16
	s_nop 1
	v_writelane_b32 v254, s49, 17
	v_cmp_lt_u32_e64 s[48:49], 17, v2
	s_nop 1
	v_writelane_b32 v254, s48, 18
	s_nop 1
	v_writelane_b32 v254, s49, 19
	v_cmp_lt_u32_e64 s[48:49], 18, v2
	s_nop 1
	v_writelane_b32 v254, s48, 20
	s_nop 1
	v_writelane_b32 v254, s49, 21
	v_cmp_lt_u32_e64 s[48:49], 19, v2
	s_nop 1
	v_writelane_b32 v254, s48, 22
	s_nop 1
	v_writelane_b32 v254, s49, 23
	v_cmp_lt_u32_e64 s[48:49], 20, v2
	s_nop 1
	v_writelane_b32 v254, s48, 24
	s_nop 1
	v_writelane_b32 v254, s49, 25
	v_cmp_lt_u32_e64 s[48:49], 21, v2
	s_nop 1
	v_writelane_b32 v254, s48, 26
	s_nop 1
	v_writelane_b32 v254, s49, 27
	v_cmp_lt_u32_e64 s[48:49], 22, v2
	s_nop 1
	v_writelane_b32 v254, s48, 28
	s_nop 1
	v_writelane_b32 v254, s49, 29
	v_cmp_lt_u32_e64 s[48:49], 24, v2
	s_nop 1
	v_writelane_b32 v254, s48, 30
	s_nop 1
	v_writelane_b32 v254, s49, 31
	v_cmp_lt_u32_e64 s[48:49], 25, v2
	s_nop 1
	v_writelane_b32 v254, s48, 32
	s_nop 1
	v_writelane_b32 v254, s49, 33
	v_cmp_lt_u32_e64 s[48:49], 26, v2
	s_nop 1
	v_writelane_b32 v254, s48, 34
	s_nop 1
	v_writelane_b32 v254, s49, 35
	v_cmp_lt_u32_e64 s[48:49], 27, v2
	v_or_b32_e32 v2, 6, v1
	v_and_b32_e32 v1, 35, v0
	v_writelane_b32 v254, s48, 36
	v_cmp_lt_u32_e64 s[70:71], 29, v2
	v_cmp_eq_u32_e64 s[72:73], 0, v1
	v_writelane_b32 v254, s49, 37
	v_cmp_lt_u32_e64 s[48:49], 8, v2
	v_mbcnt_lo_u32_b32 v1, -1, 0
	v_mbcnt_hi_u32_b32 v246, -1, v1
	v_writelane_b32 v254, s48, 38
	s_nop 1
	v_writelane_b32 v254, s49, 39
	v_cmp_lt_u32_e64 s[48:49], 9, v2
	s_nop 1
	v_writelane_b32 v254, s48, 40
	s_nop 1
	v_writelane_b32 v254, s49, 41
	v_cmp_lt_u32_e64 s[48:49], 10, v2
	s_nop 1
	v_writelane_b32 v254, s48, 42
	s_nop 1
	v_writelane_b32 v254, s49, 43
	v_cmp_lt_u32_e64 s[48:49], 11, v2
	s_nop 1
	v_writelane_b32 v254, s48, 44
	s_nop 1
	v_writelane_b32 v254, s49, 45
	v_cmp_lt_u32_e64 s[48:49], 12, v2
	s_nop 1
	v_writelane_b32 v254, s48, 46
	s_nop 1
	v_writelane_b32 v254, s49, 47
	v_cmp_lt_u32_e64 s[48:49], 13, v2
	s_nop 1
	v_writelane_b32 v254, s48, 48
	s_nop 1
	v_writelane_b32 v254, s49, 49
	v_cmp_lt_u32_e64 s[48:49], 14, v2
	s_nop 1
	v_writelane_b32 v254, s48, 50
	s_nop 1
	v_writelane_b32 v254, s49, 51
	v_cmp_lt_u32_e64 s[48:49], 16, v2
	s_nop 1
	v_writelane_b32 v254, s48, 52
	s_nop 1
	v_writelane_b32 v254, s49, 53
	v_cmp_lt_u32_e64 s[48:49], 17, v2
	s_nop 1
	v_writelane_b32 v254, s48, 54
	s_nop 1
	v_writelane_b32 v254, s49, 55
	v_cmp_lt_u32_e64 s[48:49], 18, v2
	s_nop 1
	v_writelane_b32 v254, s48, 56
	s_nop 1
	v_writelane_b32 v254, s49, 57
	v_cmp_lt_u32_e64 s[48:49], 19, v2
	s_nop 1
	v_writelane_b32 v254, s48, 58
	s_nop 1
	v_writelane_b32 v254, s49, 59
	v_cmp_lt_u32_e64 s[48:49], 20, v2
	s_nop 1
	v_writelane_b32 v254, s48, 60
	s_nop 1
	v_writelane_b32 v254, s49, 61
	v_cmp_lt_u32_e64 s[48:49], 21, v2
	s_nop 1
	v_writelane_b32 v254, s48, 62
	s_nop 1
	v_writelane_b32 v254, s49, 63
	v_cmp_lt_u32_e64 s[48:49], 22, v2
	s_nop 1
	v_writelane_b32 v255, s48, 0
	s_nop 1
	v_writelane_b32 v255, s49, 1
	v_cmp_lt_u32_e64 s[48:49], 24, v2
	s_nop 1
	v_writelane_b32 v255, s48, 2
	s_nop 1
	v_writelane_b32 v255, s49, 3
	v_cmp_lt_u32_e64 s[48:49], 25, v2
	s_nop 1
	v_writelane_b32 v255, s48, 4
	s_nop 1
	v_writelane_b32 v255, s49, 5
	v_cmp_lt_u32_e64 s[48:49], 26, v2
	s_nop 1
	v_writelane_b32 v255, s48, 6
	s_nop 1
	v_writelane_b32 v255, s49, 7
	v_cmp_lt_u32_e64 s[48:49], 27, v2
	s_nop 1
	v_writelane_b32 v255, s48, 8
	s_nop 1
	v_writelane_b32 v255, s49, 9
	v_cmp_lt_u32_e64 s[48:49], 28, v2
	v_lshlrev_b64 v[2:3], v135, -1
	v_not_b32_e32 v111, v3
	v_writelane_b32 v255, s48, 10
	v_not_b32_e32 v118, v2
	s_nop 0
	v_writelane_b32 v255, s49, 11
	s_mov_b64 s[48:49], exec
	s_mov_b64 exec, 1
	v_mov_b32_e32 v1, 0
	v_mov_b32_e32 v2, 1
	ds_add_rtn_u32 v2, v1, v2
	s_waitcnt lgkmcnt(0)
	v_readfirstlane_b32 s47, v2
	s_mov_b64 exec, s[48:49]
	s_cmpk_lt_u32 s47, 0x80
	s_cselect_b64 s[8:9], -1, 0
	s_branch .LBB0_477
.LBB0_476:
	s_add_i32 s64, s64, 1
	s_mov_b64 s[48:49], exec
	s_mov_b64 exec, 1
	v_mov_b32_e32 v1, 0
	v_mov_b32_e32 v2, 1
	ds_add_rtn_u32 v2, v1, v2
	s_waitcnt lgkmcnt(0)
	v_readfirstlane_b32 s47, v2
	s_mov_b64 exec, s[48:49]
	s_cmpk_lt_u32 s47, 0x80
	s_cselect_b64 s[8:9], -1, 0
	s_cmp_lt_i32 s63, s58
	s_cselect_b64 s[10:11], -1, 0
	s_or_b64 s[48:49], s[8:9], s[10:11]
	s_andn2_b64 vcc, exec, s[48:49]
	s_cbranch_vccnz .LBB0_659

; DI size_t sc_rowoff(int b, int t) { const int c = t >> 6; return (size_t)b * SC_PB + (size_t)4096 * (c * (c + 1) / 2) + (size_t)(t & 63) * (64 * (c + 1)); }
; DI void select_row(const float* SC, unsigned* dmask, int b, int t, int lane) {
;     unsigned* dm = dmask + ((size_t)b * SEQ + t) * 64;
;     const int nvalid = t + 1;
;     if (nvalid <= 256) {
;         const int w = lane;
;         const int lo = 32 * w; unsigned bits = 0u;
;         if (lo + 31 <= t) bits = 0xffffffffu; else if (lo <= t) bits = (2u << (t - lo)) - 1u;
;         dm[w] = bits; return;
;     }
;     const int nch = (nvalid + 255) >> 8;
;     const float* srow = SC + sc_rowoff(b, t) + 4 * lane;
;     unsigned u[8][4];
; #pragma unroll
;     for (int k = 0; k < 8; ++k) {
;         if (k < nch) {
;             const f32x4 v = *(const f32x4*)(srow + 256 * k);
; #pragma unroll
;             for (int e = 0; e < 4; ++e) { const unsigned bits = __builtin_bit_cast(unsigned, v[e] + 0.0f); const unsigned key = ((int)bits < 0) ? ~bits : (bits | 0x80000000u);
;                 u[k][e] = (256 * k + 4 * lane + e <= t) ? key : 0u; }
;         } else { u[k][0] = 0u; u[k][1] = 0u; u[k][2] = 0u; u[k][3] = 0u; }
;     }
; __global__ void __launch_bounds__(NTHR, 2) fwd_kernel(Args a) {
;     ...
;             if (ci < ncmp && (i >= nrow || (i % stride) == phase)) { const int task = gw + ci * NGW; ++ci;
;                 cmp_task(Z, KCC, VCT, OCMP, SELM, task >> 9, (task >> 8) & 1, (task + 64 * (task >> 11)) & 255, lane); }
;             if (i < nrow) { const int r = gw + i * NGW; select_row(SC, DMASK, r & 15, r >> 4, lane); }
.LBB0_535:
	s_and_b64 vcc, exec, s[76:77]
	s_cbranch_vccnz .LBB0_476
	s_lshr_b32 s10, s47, 3
	s_sub_i32 s10, 15, s10
	s_lshl_b32 s10, s10, 11
	s_and_b32 s11, s47, 7
	s_add_i32 s11, s11, s10
	s_and_b32 s10, s92, -8
	s_add_i32 s11, s11, s10
	s_and_b32 s10, s11, 15
	s_ashr_i32 s65, s11, 4
	s_lshl_b32 s8, s10, 11
	s_ashr_i32 s9, s65, 31
	s_add_u32 s8, s8, s65
	s_addc_u32 s9, 0, s9
	s_lshl_b64 s[8:9], s[8:9], 8
	s_add_u32 s48, s21, s8
	s_addc_u32 s49, s68, s9
	s_cmpk_gt_i32 s65, 0xff
	s_mov_b64 s[8:9], -1
	s_cbranch_scc0 .LBB0_657
	s_lshr_b32 s8, s65, 6
	s_add_i32 s9, s8, 1
	s_mul_i32 s8, s9, s8
	s_lshr_b32 s14, s8, 1
	s_bfe_u32 s8, s11, 0x60004
	s_lshl_b32 s11, s9, 6
	s_mul_hi_u32 s9, s11, s8
	s_mul_i32 s8, s11, s8
	s_lshl_b64 s[8:9], s[8:9], 2
	s_add_u32 s8, s44, s8
	s_addc_u32 s9, s45, s9
	s_mul_i32 s10, s10, 0x840000
	s_add_u32 s10, s8, s10
	s_addc_u32 s11, s9, 0
	s_lshl_b64 s[8:9], s[14:15], 14
	s_add_u32 s8, s10, s8
	s_addc_u32 s9, s11, s9
	global_load_dwordx4 v[6:9], v120, s[8:9]
	global_load_dwordx4 v[2:5], v120, s[8:9] offset:1024
	s_add_u32 s98, s8, 0x1000
	s_addc_u32 s99, s9, 0
	s_cmpk_lt_u32 s65, 0x200
	s_cbranch_scc1 .Lsel_pf_done
	global_load_dwordx4 v[150:153], v120, s[8:9] offset:2048
	s_cmpk_lt_u32 s65, 0x300
	s_cbranch_scc1 .Lsel_pf_done
	global_load_dwordx4 v[154:157], v120, s[8:9] offset:3072
	s_cmpk_lt_u32 s65, 0x400
	s_cbranch_scc1 .Lsel_pf_done
	global_load_dwordx4 v[158:161], v120, s[98:99]
	s_cmpk_lt_u32 s65, 0x500
	s_cbranch_scc1 .Lsel_pf_done
	global_load_dwordx4 v[162:165], v120, s[98:99] offset:1024
	s_cmpk_lt_u32 s65, 0x600
	s_cbranch_scc1 .Lsel_pf_done
	global_load_dwordx4 v[166:169], v120, s[98:99] offset:2048
	s_cmpk_lt_u32 s65, 0x700
	s_cbranch_scc1 .Lsel_pf_done
	global_load_dwordx4 v[170:173], v120, s[98:99] offset:3072
